# P2/P4 waits made independent of the relative completion order of loads and stores (V/gate requests complete before the state stores; one wait for the o-gate rows) - run 1
# speedup vs baseline: 1.0038x; 1.0038x over previous
.LBB0_285:
	s_or_b64 exec, exec, s[44:45]
	s_add_i32 s42, s42, s90
	s_cmpk_gt_i32 s42, 0x7ff
	s_cbranch_scc1 .LBB0_309
.LBB0_286:
	s_waitcnt lgkmcnt(0)
	s_barrier
	s_and_saveexec_b64 s[46:47], s[16:17]
	s_cbranch_execz .Lp2_w_skip
	global_load_dwordx4 v[48:51], v189, s[68:69]
	global_load_dwordx4 v[56:59], v189, s[70:71]
	global_load_dwordx4 v[52:55], v193, s[68:69]
	global_load_dwordx4 v[60:63], v194, s[68:69]
	global_load_dwordx4 v[64:67], v195, s[68:69]
	global_load_dwordx4 v[28:31], v189, s[68:69] offset:16
	global_load_dwordx4 v[32:35], v189, s[70:71] offset:16
	global_load_dwordx4 v[36:39], v193, s[68:69] offset:16
	global_load_dwordx4 v[40:43], v194, s[68:69] offset:16
	global_load_dwordx4 v[44:47], v195, s[68:69] offset:16

.Lp2_cw_done:
	v_lshlrev_b32_e32 v110, 16, v218
	v_and_b32_e32 v111, 0xffff0000, v218
	v_lshlrev_b32_e32 v112, 16, v230
	v_and_b32_e32 v113, 0xffff0000, v230
	v_lshlrev_b32_e32 v114, 16, v226
	v_and_b32_e32 v115, 0xffff0000, v226
	v_lshlrev_b32_e32 v122, 16, v222
	v_and_b32_e32 v123, 0xffff0000, v222
	s_waitcnt lgkmcnt(0)
	v_mul_f32_e32 v24, 0x3d93cd3a, v236
	v_mul_f32_e32 v20, 0x3d93cd3a, v237
	v_mul_f32_e32 v16, 0x3d93cd3a, v238
	v_mul_f32_e32 v12, 0x3d93cd3a, v239
	v_lshlrev_b32_e32 v120, 16, v206
	v_and_b32_e32 v121, 0xffff0000, v206
	v_lshlrev_b32_e32 v116, 16, v214
	v_and_b32_e32 v117, 0xffff0000, v214
	v_lshlrev_b32_e32 v118, 16, v210
	v_and_b32_e32 v119, 0xffff0000, v210
	v_pk_fma_f32 v[120:121], v[48:49], v[120:121], v[56:57]
	v_pk_fma_f32 v[124:125], v[48:49], v[116:117], v[56:57]
	v_pk_fma_f32 v[126:127], v[48:49], v[118:119], v[56:57]
	v_pk_fma_f32 v[48:49], v[48:49], v[110:111], v[56:57]
	v_pk_fma_f32 v[118:119], v[52:53], v[118:119], v[120:121]
	v_pk_fma_f32 v[56:57], v[52:53], v[116:117], v[126:127]
	v_pk_fma_f32 v[120:121], v[52:53], v[110:111], v[124:125]
	v_pk_fma_f32 v[48:49], v[52:53], v[112:113], v[48:49]
	v_pk_fma_f32 v[52:53], v[60:61], v[116:117], v[118:119]
	v_pk_fma_f32 v[56:57], v[60:61], v[110:111], v[56:57]
	v_pk_fma_f32 v[116:117], v[60:61], v[112:113], v[120:121]
	v_pk_fma_f32 v[52:53], v[64:65], v[110:111], v[52:53]
	v_pk_fma_f32 v[48:49], v[60:61], v[114:115], v[48:49]
	v_pk_fma_f32 v[56:57], v[64:65], v[112:113], v[56:57]
	v_pk_fma_f32 v[60:61], v[64:65], v[114:115], v[116:117]
	v_mul_f32_e32 v0, 0xbfb8aa3b, v52
	v_mul_f32_e32 v4, 0xbfb8aa3b, v53
	v_pk_fma_f32 v[48:49], v[64:65], v[122:123], v[48:49]
	v_mul_f32_e32 v64, 0xbfb8aa3b, v57
	v_mul_f32_e32 v65, 0xbfb8aa3b, v60
	v_exp_f32_e32 v0, v0
	v_exp_f32_e32 v4, v4
	v_exp_f32_e32 v64, v64
	v_exp_f32_e32 v65, v65
	v_mul_f32_e32 v8, 0xbfb8aa3b, v56
	v_exp_f32_e32 v8, v8
	v_mul_f32_e32 v84, 0xbfb8aa3b, v61
	v_mul_f32_e32 v111, 0xbfb8aa3b, v49
	v_add_f32_e32 v0, 1.0, v0
	v_add_f32_e32 v4, 1.0, v4
	v_mul_f32_e32 v110, 0xbfb8aa3b, v48
	v_exp_f32_e32 v84, v84
	v_exp_f32_e32 v115, v111
	v_add_f32_e32 v111, 1.0, v64
	v_add_f32_e32 v112, 1.0, v65
	v_rcp_f32_e32 v64, v0
	v_rcp_f32_e32 v65, v4
	v_exp_f32_e32 v114, v110
	v_add_f32_e32 v8, 1.0, v8
	v_rcp_f32_e32 v110, v8
	v_rcp_f32_e32 v111, v111
	v_add_f32_e32 v84, 1.0, v84
	v_pk_mul_f32 v[52:53], v[52:53], v[64:65]
	v_rcp_f32_e32 v112, v112
	v_rcp_f32_e32 v113, v84
	v_pk_mul_f32 v[52:53], v[24:25], v[52:53] op_sel_hi:[0,1]
	v_add_f32_e32 v8, 1.0, v114
	v_cvt_pk_bf16_f32 v4, v52, v53
	v_rcp_f32_e32 v52, v8
	v_add_f32_e32 v8, 1.0, v115
	v_pk_mul_f32 v[56:57], v[56:57], v[110:111]
	v_rcp_f32_e32 v53, v8
	v_pk_mul_f32 v[56:57], v[20:21], v[56:57] op_sel_hi:[0,1]
	v_lshlrev_b32_e32 v116, 16, v207
	v_and_b32_e32 v117, 0xffff0000, v207
	v_cvt_pk_bf16_f32 v0, v56, v57
	v_pk_mul_f32 v[56:57], v[60:61], v[112:113]
	v_lshlrev_b32_e32 v112, 16, v211
	v_and_b32_e32 v113, 0xffff0000, v211
	v_pk_fma_f32 v[116:117], v[50:51], v[116:117], v[58:59]
	v_lshlrev_b32_e32 v64, 16, v215
	v_and_b32_e32 v65, 0xffff0000, v215
	v_pk_fma_f32 v[114:115], v[50:51], v[112:113], v[58:59]
	v_pk_fma_f32 v[112:113], v[54:55], v[112:113], v[116:117]
	v_pk_mul_f32 v[48:49], v[48:49], v[52:53]
	v_lshlrev_b32_e32 v52, 16, v219
	v_and_b32_e32 v53, 0xffff0000, v219
	v_pk_fma_f32 v[112:113], v[62:63], v[64:65], v[112:113]
	v_pk_mul_f32 v[56:57], v[16:17], v[56:57] op_sel_hi:[0,1]
	v_pk_fma_f32 v[112:113], v[66:67], v[52:53], v[112:113]
	v_pk_fma_f32 v[110:111], v[50:51], v[64:65], v[58:59]
	v_mul_f32_e32 v1, 0xbfb8aa3b, v112
	v_exp_f32_e32 v1, v1
	v_mul_f32_e32 v5, 0xbfb8aa3b, v113
	v_exp_f32_e32 v5, v5
	v_pk_fma_f32 v[64:65], v[54:55], v[64:65], v[114:115]
	v_cvt_pk_bf16_f32 v8, v56, v57
	v_lshlrev_b32_e32 v56, 16, v231
	v_and_b32_e32 v57, 0xffff0000, v231
	v_pk_fma_f32 v[64:65], v[62:63], v[52:53], v[64:65]
	v_add_f32_e32 v1, 1.0, v1
	v_pk_fma_f32 v[64:65], v[66:67], v[56:57], v[64:65]
	v_rcp_f32_e32 v114, v1
	v_add_f32_e32 v1, 1.0, v5
	v_mul_f32_e32 v5, 0xbfb8aa3b, v64
	v_exp_f32_e32 v5, v5
	v_mul_f32_e32 v9, 0xbfb8aa3b, v65
	v_exp_f32_e32 v9, v9
	v_pk_fma_f32 v[110:111], v[54:55], v[52:53], v[110:111]
	v_lshlrev_b32_e32 v60, 16, v227
	v_and_b32_e32 v61, 0xffff0000, v227
	v_rcp_f32_e32 v115, v1
	v_add_f32_e32 v1, 1.0, v5
	v_pk_fma_f32 v[110:111], v[62:63], v[56:57], v[110:111]
	v_rcp_f32_e32 v116, v1
	v_add_f32_e32 v1, 1.0, v9
	v_pk_fma_f32 v[110:111], v[66:67], v[60:61], v[110:111]
	v_rcp_f32_e32 v117, v1
	v_mul_f32_e32 v1, 0xbfb8aa3b, v110
	v_exp_f32_e32 v9, v1
	v_mul_f32_e32 v1, 0xbfb8aa3b, v111
	v_pk_mul_f32 v[48:49], v[12:13], v[48:49] op_sel_hi:[0,1]
	v_pk_mul_f32 v[112:113], v[112:113], v[114:115]
	v_exp_f32_e32 v13, v1
	v_pk_fma_f32 v[50:51], v[50:51], v[52:53], v[58:59]
	v_pk_mul_f32 v[112:113], v[24:25], v[112:113] op_sel_hi:[0,1]
	v_pk_fma_f32 v[50:51], v[54:55], v[56:57], v[50:51]
	v_cvt_pk_bf16_f32 v5, v112, v113
	v_pk_mul_f32 v[64:65], v[64:65], v[116:117]
	v_lshlrev_b32_e32 v112, 16, v223
	v_and_b32_e32 v113, 0xffff0000, v223
	v_pk_fma_f32 v[50:51], v[62:63], v[60:61], v[50:51]
	v_pk_mul_f32 v[64:65], v[20:21], v[64:65] op_sel_hi:[0,1]
	v_add_f32_e32 v9, 1.0, v9
	v_pk_fma_f32 v[50:51], v[66:67], v[112:113], v[50:51]
	v_cvt_pk_bf16_f32 v1, v64, v65
	v_rcp_f32_e32 v64, v9
	v_add_f32_e32 v9, 1.0, v13
	v_mul_f32_e32 v13, 0xbfb8aa3b, v50
	v_exp_f32_e32 v13, v13
	v_mul_f32_e32 v17, 0xbfb8aa3b, v51
	v_exp_f32_e32 v17, v17
	v_rcp_f32_e32 v65, v9
	v_add_f32_e32 v9, 1.0, v13
	v_rcp_f32_e32 v52, v9
	v_add_f32_e32 v9, 1.0, v17
	v_rcp_f32_e32 v53, v9
	v_lshlrev_b32_e32 v66, 16, v208
	v_and_b32_e32 v67, 0xffff0000, v208
	v_lshlrev_b32_e32 v62, 16, v212
	v_and_b32_e32 v63, 0xffff0000, v212
	v_pk_fma_f32 v[66:67], v[28:29], v[66:67], v[32:33]
	v_pk_mul_f32 v[54:55], v[110:111], v[64:65]
	v_lshlrev_b32_e32 v58, 16, v216
	v_and_b32_e32 v59, 0xffff0000, v216
	v_pk_fma_f32 v[64:65], v[28:29], v[62:63], v[32:33]
	v_pk_fma_f32 v[62:63], v[36:37], v[62:63], v[66:67]
	v_pk_mul_f32 v[50:51], v[50:51], v[52:53]
	v_lshlrev_b32_e32 v52, 16, v220
	v_and_b32_e32 v53, 0xffff0000, v220
	v_pk_fma_f32 v[62:63], v[40:41], v[58:59], v[62:63]
	v_pk_mul_f32 v[54:55], v[16:17], v[54:55] op_sel_hi:[0,1]
	v_pk_fma_f32 v[62:63], v[44:45], v[52:53], v[62:63]
	v_pk_fma_f32 v[60:61], v[28:29], v[58:59], v[32:33]
	v_mul_f32_e32 v2, 0xbfb8aa3b, v62
	v_exp_f32_e32 v2, v2
	v_mul_f32_e32 v6, 0xbfb8aa3b, v63
	v_exp_f32_e32 v6, v6
	v_pk_fma_f32 v[58:59], v[36:37], v[58:59], v[64:65]
	v_cvt_pk_bf16_f32 v9, v54, v55
	v_lshlrev_b32_e32 v54, 16, v232
	v_and_b32_e32 v55, 0xffff0000, v232
	v_pk_fma_f32 v[58:59], v[40:41], v[52:53], v[58:59]
	v_add_f32_e32 v2, 1.0, v2
	v_pk_fma_f32 v[58:59], v[44:45], v[54:55], v[58:59]
	v_rcp_f32_e32 v64, v2
	v_add_f32_e32 v2, 1.0, v6
	v_mul_f32_e32 v6, 0xbfb8aa3b, v58
	v_exp_f32_e32 v6, v6
	v_mul_f32_e32 v10, 0xbfb8aa3b, v59
	v_exp_f32_e32 v10, v10
	v_pk_fma_f32 v[60:61], v[36:37], v[52:53], v[60:61]
	v_lshlrev_b32_e32 v56, 16, v228
	v_and_b32_e32 v57, 0xffff0000, v228
	v_rcp_f32_e32 v65, v2
	v_add_f32_e32 v2, 1.0, v6
	v_pk_fma_f32 v[60:61], v[40:41], v[54:55], v[60:61]
	v_rcp_f32_e32 v66, v2
	v_add_f32_e32 v2, 1.0, v10
	v_pk_fma_f32 v[60:61], v[44:45], v[56:57], v[60:61]
	v_rcp_f32_e32 v67, v2
	v_mul_f32_e32 v2, 0xbfb8aa3b, v60
	v_exp_f32_e32 v10, v2
	v_mul_f32_e32 v2, 0xbfb8aa3b, v61
	v_pk_mul_f32 v[50:51], v[12:13], v[50:51] op_sel_hi:[0,1]
	v_pk_mul_f32 v[62:63], v[62:63], v[64:65]
	v_exp_f32_e32 v13, v2
	v_pk_fma_f32 v[28:29], v[28:29], v[52:53], v[32:33]
	v_pk_mul_f32 v[62:63], v[24:25], v[62:63] op_sel_hi:[0,1]
	v_pk_fma_f32 v[28:29], v[36:37], v[54:55], v[28:29]
	v_cvt_pk_bf16_f32 v6, v62, v63
	v_pk_mul_f32 v[58:59], v[58:59], v[66:67]
	v_lshlrev_b32_e32 v62, 16, v224
	v_and_b32_e32 v63, 0xffff0000, v224
	v_pk_fma_f32 v[28:29], v[40:41], v[56:57], v[28:29]
	v_pk_mul_f32 v[58:59], v[20:21], v[58:59] op_sel_hi:[0,1]
	v_add_f32_e32 v10, 1.0, v10
	v_pk_fma_f32 v[28:29], v[44:45], v[62:63], v[28:29]
	v_cvt_pk_bf16_f32 v2, v58, v59
	v_rcp_f32_e32 v58, v10
	v_add_f32_e32 v10, 1.0, v13
	v_mul_f32_e32 v13, 0xbfb8aa3b, v28
	v_exp_f32_e32 v13, v13
	v_mul_f32_e32 v14, 0xbfb8aa3b, v29
	v_exp_f32_e32 v14, v14
	v_rcp_f32_e32 v59, v10
	v_add_f32_e32 v10, 1.0, v13
	v_rcp_f32_e32 v32, v10
	v_add_f32_e32 v10, 1.0, v14
	v_rcp_f32_e32 v33, v10
	v_lshlrev_b32_e32 v52, 16, v209
	v_and_b32_e32 v53, 0xffff0000, v209
	v_lshlrev_b32_e32 v40, 16, v213
	v_and_b32_e32 v41, 0xffff0000, v213
	v_pk_fma_f32 v[52:53], v[30:31], v[52:53], v[34:35]
	v_pk_mul_f32 v[28:29], v[28:29], v[32:33]
	v_lshlrev_b32_e32 v32, 16, v217
	v_and_b32_e32 v33, 0xffff0000, v217
	v_pk_fma_f32 v[44:45], v[30:31], v[40:41], v[34:35]
	v_pk_fma_f32 v[40:41], v[38:39], v[40:41], v[52:53]
	v_lshlrev_b32_e32 v14, 16, v221
	v_and_b32_e32 v15, 0xffff0000, v221
	v_pk_fma_f32 v[40:41], v[42:43], v[32:33], v[40:41]
	v_pk_mul_f32 v[36:37], v[60:61], v[58:59]
	v_pk_fma_f32 v[40:41], v[46:47], v[14:15], v[40:41]
	v_pk_mul_f32 v[36:37], v[16:17], v[36:37] op_sel_hi:[0,1]
	v_mul_f32_e32 v3, 0xbfb8aa3b, v40
	v_exp_f32_e32 v3, v3
	v_mul_f32_e32 v7, 0xbfb8aa3b, v41
	v_exp_f32_e32 v7, v7
	v_cvt_pk_bf16_f32 v10, v36, v37
	v_pk_fma_f32 v[36:37], v[30:31], v[32:33], v[34:35]
	v_pk_fma_f32 v[32:33], v[38:39], v[32:33], v[44:45]
	v_lshlrev_b32_e32 v26, 16, v233
	v_and_b32_e32 v27, 0xffff0000, v233
	v_pk_fma_f32 v[32:33], v[42:43], v[14:15], v[32:33]
	v_add_f32_e32 v3, 1.0, v3
	v_pk_fma_f32 v[32:33], v[46:47], v[26:27], v[32:33]
	v_rcp_f32_e32 v44, v3
	v_add_f32_e32 v3, 1.0, v7
	v_mul_f32_e32 v7, 0xbfb8aa3b, v32
	v_exp_f32_e32 v7, v7
	v_mul_f32_e32 v11, 0xbfb8aa3b, v33
	v_exp_f32_e32 v11, v11
	v_rcp_f32_e32 v45, v3
	v_add_f32_e32 v3, 1.0, v7
	v_rcp_f32_e32 v52, v3
	v_add_f32_e32 v3, 1.0, v11
	v_rcp_f32_e32 v53, v3
	v_pk_mul_f32 v[40:41], v[40:41], v[44:45]
	v_lshlrev_b32_e32 v22, 16, v229
	v_pk_mul_f32 v[24:25], v[24:25], v[40:41] op_sel_hi:[0,1]
	v_cvt_pk_bf16_f32 v7, v24, v25
	v_pk_mul_f32 v[24:25], v[32:33], v[52:53]
	v_and_b32_e32 v23, 0xffff0000, v229
	v_pk_mul_f32 v[20:21], v[20:21], v[24:25] op_sel_hi:[0,1]
	v_pk_fma_f32 v[24:25], v[38:39], v[14:15], v[36:37]
	v_pk_mul_f32 v[28:29], v[12:13], v[28:29] op_sel_hi:[0,1]
	v_pk_fma_f32 v[24:25], v[42:43], v[26:27], v[24:25]
	v_pk_fma_f32 v[14:15], v[30:31], v[14:15], v[34:35]
	v_pk_fma_f32 v[24:25], v[46:47], v[22:23], v[24:25]
	v_pk_fma_f32 v[14:15], v[38:39], v[26:27], v[14:15]
	v_mul_f32_e32 v3, 0xbfb8aa3b, v24
	v_exp_f32_e32 v11, v3
	v_mul_f32_e32 v3, 0xbfb8aa3b, v25
	v_exp_f32_e32 v13, v3
	v_cvt_pk_bf16_f32 v3, v20, v21
	v_lshlrev_b32_e32 v20, 16, v225
	v_and_b32_e32 v21, 0xffff0000, v225
	v_pk_fma_f32 v[14:15], v[42:43], v[22:23], v[14:15]
	v_add_f32_e32 v11, 1.0, v11
	v_pk_fma_f32 v[14:15], v[46:47], v[20:21], v[14:15]
	v_rcp_f32_e32 v18, v11
	v_add_f32_e32 v11, 1.0, v13
	v_mul_f32_e32 v13, 0xbfb8aa3b, v14
	v_exp_f32_e32 v13, v13
	v_mul_f32_e32 v17, 0xbfb8aa3b, v15
	v_exp_f32_e32 v17, v17
	v_rcp_f32_e32 v19, v11
	v_add_f32_e32 v11, 1.0, v13
	v_rcp_f32_e32 v20, v11
	v_add_f32_e32 v11, 1.0, v17
	v_rcp_f32_e32 v21, v11
	v_pk_mul_f32 v[18:19], v[24:25], v[18:19]
	v_pk_mul_f32 v[14:15], v[14:15], v[20:21]
	v_pk_mul_f32 v[16:17], v[16:17], v[18:19] op_sel_hi:[0,1]
	v_cvt_pk_bf16_f32 v11, v16, v17
	v_pk_mul_f32 v[16:17], v[12:13], v[14:15] op_sel_hi:[0,1]
	v_cvt_pk_bf16_f32 v12, v48, v49
	v_cvt_pk_bf16_f32 v13, v50, v51
	v_cvt_pk_bf16_f32 v14, v28, v29
	v_cvt_pk_bf16_f32 v15, v16, v17
	ds_write_b128 v104, v[4:7]
	ds_write_b128 v104, v[0:3] offset:400
	ds_write_b128 v104, v[8:11] offset:800
	ds_write_b128 v104, v[12:15] offset:1200
.LBB0_305:
	s_or_b64 exec, exec, s[46:47]
	s_add_i32 s34, s42, s90
	s_cmpk_gt_i32 s34, 0x7ff
	s_cbranch_scc1 .Lp2_pf_none
	s_and_saveexec_b64 s[46:47], s[16:17]
	s_cbranch_execz .Lp2_pf_r_b
	v_add_u32_e32 v199, s72, v94
	v_add_u32_e32 v200, s65, v92
	v_cmp_ne_u32_e32 vcc, 0, v200
	v_add_u32_e32 v201, s44, v200
	v_mul_lo_u32 v201, v201, s54
	v_lshl_add_u32 v201, v199, 1, v201
	v_lshlrev_b32_e32 v189, 2, v199
	v_add_u32_e32 v193, 0x1800, v189
	v_add_u32_e32 v194, 0x3000, v189
	v_add_u32_e32 v195, 0x4800, v189
	v_add_u32_e32 v196, 0xffffac00, v201
	v_add_u32_e32 v197, 0xffffc800, v201
	v_add_u32_e32 v198, 0xffffe400, v201
	v_add_u32_e32 v202, 0x1c00, v201
	v_add_u32_e32 v203, 0x3800, v201
	v_add_u32_e32 v200, 0x5400, v201
	v_mov_b32_e32 v206, 0
	v_mov_b32_e32 v207, 0
	v_mov_b32_e32 v208, 0
	v_mov_b32_e32 v209, 0
	v_mov_b32_e32 v210, 0
	v_mov_b32_e32 v211, 0
	v_mov_b32_e32 v212, 0
	v_mov_b32_e32 v213, 0
	v_mov_b32_e32 v214, 0
	v_mov_b32_e32 v215, 0
	v_mov_b32_e32 v216, 0
	v_mov_b32_e32 v217, 0
	s_and_b64 exec, exec, vcc
	global_load_dwordx4 v[206:209], v196, s[60:61]
	global_load_dwordx4 v[210:213], v197, s[60:61]
	global_load_dwordx4 v[214:217], v198, s[60:61]
	s_mov_b64 exec, s[16:17]
	global_load_dwordx4 v[218:221], v201, s[60:61]
	global_load_dwordx4 v[230:233], v202, s[60:61]
	global_load_dwordx4 v[226:229], v203, s[60:61]
	global_load_dwordx4 v[222:225], v200, s[60:61]
.Lp2_pf_r_b:
	s_or_b64 exec, exec, s[46:47]
	s_cmpk_lt_u32 s64, 0x180
	s_cbranch_scc1 .Lp2_pw_c
	s_waitcnt vmcnt(0)
	s_branch .Lp2_pf_none

.Lp2_pf_none:
	s_and_saveexec_b64 s[46:47], s[14:15]
	s_cbranch_execz .Lp2_ml_skip
	s_ashr_i32 s43, s42, 31
	s_lshl_b64 s[48:49], s[42:43], 2
	s_add_u32 s76, s50, s48
	s_addc_u32 s77, s51, s49
	s_add_u32 s48, s52, s48
	s_addc_u32 s49, s53, s49
	global_store_dword v85, v234, s[76:77]
	global_store_dword v85, v235, s[48:49]

.LBB0_506:
	s_or_b64 exec, exec, s[36:37]
	s_waitcnt lgkmcnt(0)
	ds_read_b128 v[72:75], v173
	ds_read_b128 v[84:87], v173 offset:6400
	ds_read_b128 v[184:187], v173 offset:12800
	ds_read_b128 v[196:199], v173 offset:19200
	s_mul_i32 s36, s63, 0x60
	s_mulk_i32 s63, 0xc0
	s_lshl_b32 s37, s65, 6
	s_add_i32 s62, s62, s90
	s_waitcnt lgkmcnt(3)
	v_mfma_f32_16x16x32_bf16 v[76:79], v[72:75], v[60:63], 0
	v_mfma_f32_16x16x32_bf16 v[80:83], v[72:75], v[64:67], 0
	v_mfma_f32_16x16x32_bf16 v[72:75], v[72:75], v[68:71], 0
	s_waitcnt lgkmcnt(2)
	v_mfma_f32_16x16x32_bf16 v[176:179], v[84:87], v[60:63], 0
	v_mfma_f32_16x16x32_bf16 v[180:183], v[84:87], v[64:67], 0
	v_mfma_f32_16x16x32_bf16 v[84:87], v[84:87], v[68:71], 0
	s_waitcnt lgkmcnt(1)
	v_mfma_f32_16x16x32_bf16 v[188:191], v[184:187], v[60:63], 0
	v_mfma_f32_16x16x32_bf16 v[192:195], v[184:187], v[64:67], 0
	v_mfma_f32_16x16x32_bf16 v[184:187], v[184:187], v[68:71], 0
	s_waitcnt lgkmcnt(0)
	v_mfma_f32_16x16x32_bf16 v[60:63], v[196:199], v[60:63], 0
	v_mfma_f32_16x16x32_bf16 v[64:67], v[196:199], v[64:67], 0
	v_mfma_f32_16x16x32_bf16 v[68:71], v[196:199], v[68:71], 0
	ds_read_b128 v[196:199], v173 offset:64
	s_waitcnt lgkmcnt(0)
	v_mfma_f32_16x16x32_bf16 v[76:79], v[196:199], v[48:51], v[76:79]
	v_mfma_f32_16x16x32_bf16 v[80:83], v[196:199], v[52:55], v[80:83]
	v_mfma_f32_16x16x32_bf16 v[72:75], v[196:199], v[56:59], v[72:75]
	ds_read_b128 v[196:199], v173 offset:6464
	s_waitcnt lgkmcnt(0)
	v_mfma_f32_16x16x32_bf16 v[176:179], v[196:199], v[48:51], v[176:179]
	v_mfma_f32_16x16x32_bf16 v[180:183], v[196:199], v[52:55], v[180:183]
	v_mfma_f32_16x16x32_bf16 v[84:87], v[196:199], v[56:59], v[84:87]
	ds_read_b128 v[196:199], v173 offset:12864
	s_waitcnt lgkmcnt(0)
	v_mfma_f32_16x16x32_bf16 v[188:191], v[196:199], v[48:51], v[188:191]
	v_mfma_f32_16x16x32_bf16 v[192:195], v[196:199], v[52:55], v[192:195]
	v_mfma_f32_16x16x32_bf16 v[184:187], v[196:199], v[56:59], v[184:187]
	ds_read_b128 v[196:199], v173 offset:19264
	s_waitcnt lgkmcnt(0)
	v_mfma_f32_16x16x32_bf16 v[48:51], v[196:199], v[48:51], v[60:63]
	s_nop 2
	ds_read_b128 v[60:63], v173 offset:128
	v_mfma_f32_16x16x32_bf16 v[52:55], v[196:199], v[52:55], v[64:67]
	v_mfma_f32_16x16x32_bf16 v[56:59], v[196:199], v[56:59], v[68:71]
	s_waitcnt lgkmcnt(0)
	v_mfma_f32_16x16x32_bf16 v[64:67], v[60:63], v[36:39], v[76:79]
	v_mfma_f32_16x16x32_bf16 v[68:71], v[60:63], v[40:43], v[80:83]
	v_mfma_f32_16x16x32_bf16 v[60:63], v[60:63], v[44:47], v[72:75]
	s_nop 2
	ds_read_b128 v[72:75], v173 offset:6528
	s_waitcnt lgkmcnt(0)
	v_mfma_f32_16x16x32_bf16 v[76:79], v[72:75], v[36:39], v[176:179]
	v_mfma_f32_16x16x32_bf16 v[80:83], v[72:75], v[40:43], v[180:183]
	v_mfma_f32_16x16x32_bf16 v[72:75], v[72:75], v[44:47], v[84:87]
	s_nop 2
	ds_read_b128 v[84:87], v173 offset:12928
	s_waitcnt lgkmcnt(0)
	v_mfma_f32_16x16x32_bf16 v[176:179], v[84:87], v[36:39], v[188:191]
	v_mfma_f32_16x16x32_bf16 v[180:183], v[84:87], v[40:43], v[192:195]
	v_mfma_f32_16x16x32_bf16 v[84:87], v[84:87], v[44:47], v[184:187]
	s_nop 2
	ds_read_b128 v[184:187], v173 offset:19328
	s_waitcnt lgkmcnt(0)
	v_mfma_f32_16x16x32_bf16 v[36:39], v[184:187], v[36:39], v[48:51]
	s_nop 2
	ds_read_b128 v[48:51], v173 offset:192
	v_mfma_f32_16x16x32_bf16 v[40:43], v[184:187], v[40:43], v[52:55]
	v_mfma_f32_16x16x32_bf16 v[44:47], v[184:187], v[44:47], v[56:59]
	s_waitcnt lgkmcnt(0)
	v_mfma_f32_16x16x32_bf16 v[52:55], v[48:51], v[24:27], v[64:67]
	v_mfma_f32_16x16x32_bf16 v[56:59], v[48:51], v[28:31], v[68:71]
	v_mfma_f32_16x16x32_bf16 v[48:51], v[48:51], v[32:35], v[60:63]
	s_nop 2
	ds_read_b128 v[60:63], v173 offset:6592
	s_waitcnt lgkmcnt(0)
	v_mfma_f32_16x16x32_bf16 v[64:67], v[60:63], v[24:27], v[76:79]
	v_mfma_f32_16x16x32_bf16 v[68:71], v[60:63], v[28:31], v[80:83]
	v_mfma_f32_16x16x32_bf16 v[60:63], v[60:63], v[32:35], v[72:75]
	s_nop 2
	ds_read_b128 v[72:75], v173 offset:12992
	s_waitcnt lgkmcnt(0)
	v_mfma_f32_16x16x32_bf16 v[76:79], v[72:75], v[24:27], v[176:179]
	v_mfma_f32_16x16x32_bf16 v[80:83], v[72:75], v[28:31], v[180:183]
	v_mfma_f32_16x16x32_bf16 v[72:75], v[72:75], v[32:35], v[84:87]
	s_nop 2
	ds_read_b128 v[84:87], v173 offset:19392
	s_waitcnt lgkmcnt(0)
	v_mfma_f32_16x16x32_bf16 v[24:27], v[84:87], v[24:27], v[36:39]
	s_nop 2
	ds_read_b128 v[36:39], v173 offset:256
	v_mfma_f32_16x16x32_bf16 v[28:31], v[84:87], v[28:31], v[40:43]
	v_mfma_f32_16x16x32_bf16 v[32:35], v[84:87], v[32:35], v[44:47]
	s_waitcnt lgkmcnt(0)
	v_mfma_f32_16x16x32_bf16 v[40:43], v[36:39], v[12:15], v[52:55]
	v_mfma_f32_16x16x32_bf16 v[44:47], v[36:39], v[16:19], v[56:59]
	v_mfma_f32_16x16x32_bf16 v[36:39], v[36:39], v[20:23], v[48:51]
	s_nop 2
	ds_read_b128 v[48:51], v173 offset:6656
	s_waitcnt lgkmcnt(0)
	v_mfma_f32_16x16x32_bf16 v[52:55], v[48:51], v[12:15], v[64:67]
	v_mfma_f32_16x16x32_bf16 v[56:59], v[48:51], v[16:19], v[68:71]
	v_mfma_f32_16x16x32_bf16 v[48:51], v[48:51], v[20:23], v[60:63]
	s_nop 2
	ds_read_b128 v[60:63], v173 offset:13056
	s_waitcnt lgkmcnt(0)
	v_mfma_f32_16x16x32_bf16 v[64:67], v[60:63], v[12:15], v[76:79]
	v_mfma_f32_16x16x32_bf16 v[68:71], v[60:63], v[16:19], v[80:83]
	v_mfma_f32_16x16x32_bf16 v[60:63], v[60:63], v[20:23], v[72:75]
	s_nop 2
	ds_read_b128 v[72:75], v173 offset:19456
	s_waitcnt lgkmcnt(0)
	v_mfma_f32_16x16x32_bf16 v[12:15], v[72:75], v[12:15], v[24:27]
	s_nop 2
	ds_read_b128 v[24:27], v173 offset:320
	v_mfma_f32_16x16x32_bf16 v[16:19], v[72:75], v[16:19], v[28:31]
	v_mfma_f32_16x16x32_bf16 v[20:23], v[72:75], v[20:23], v[32:35]
	s_waitcnt lgkmcnt(0)
	v_mfma_f32_16x16x32_bf16 v[28:31], v[24:27], v[0:3], v[40:43]
	v_mfma_f32_16x16x32_bf16 v[32:35], v[24:27], v[4:7], v[44:47]
	v_mfma_f32_16x16x32_bf16 v[24:27], v[24:27], v[8:11], v[36:39]
	s_nop 2
	ds_read_b128 v[36:39], v173 offset:6720
	s_waitcnt lgkmcnt(0)
	v_mfma_f32_16x16x32_bf16 v[40:43], v[36:39], v[0:3], v[52:55]
	v_mfma_f32_16x16x32_bf16 v[44:47], v[36:39], v[4:7], v[56:59]
	v_mfma_f32_16x16x32_bf16 v[36:39], v[36:39], v[8:11], v[48:51]
	s_nop 2
	ds_read_b128 v[48:51], v173 offset:13120
	s_waitcnt lgkmcnt(0)
	v_mfma_f32_16x16x32_bf16 v[52:55], v[48:51], v[0:3], v[64:67]
	v_mfma_f32_16x16x32_bf16 v[56:59], v[48:51], v[4:7], v[68:71]
	v_mfma_f32_16x16x32_bf16 v[48:51], v[48:51], v[8:11], v[60:63]
	s_nop 1
	v_add_u32_e32 v68, s36, v141
	v_lshl_add_u32 v69, s64, 5, v141
	v_lshl_add_u32 v70, s65, 5, v141
	ds_read_b128 v[60:63], v173 offset:19520
	s_waitcnt lgkmcnt(0)
	v_mfma_f32_16x16x32_bf16 v[0:3], v[60:63], v[0:3], v[12:15]
	s_nop 2
	ds_read_b128 v[12:15], v94 offset:60928
	s_lshl_b32 s36, s64, 6
	s_cmpk_lt_i32 s62, 0x400
	v_mfma_f32_16x16x32_bf16 v[4:7], v[60:63], v[4:7], v[16:19]
	v_mfma_f32_16x16x32_bf16 v[8:11], v[60:63], v[8:11], v[20:23]
	s_waitcnt lgkmcnt(0)
	s_nop 0
	v_pk_mul_f32 v[18:19], v[30:31], v[14:15]
	v_pk_mul_f32 v[16:17], v[28:29], v[12:13]
	v_pk_mul_f32 v[22:23], v[34:35], v[14:15]
	v_pk_mul_f32 v[20:21], v[32:33], v[12:13]
	v_pk_mul_f32 v[14:15], v[26:27], v[14:15]
	v_pk_mul_f32 v[12:13], v[24:25], v[12:13]
	ds_read_b128 v[24:27], v94 offset:60992
	s_waitcnt lgkmcnt(0)
	v_pk_mul_f32 v[30:31], v[42:43], v[26:27]
	v_pk_mul_f32 v[28:29], v[40:41], v[24:25]
	v_pk_mul_f32 v[34:35], v[46:47], v[26:27]
	v_pk_mul_f32 v[32:33], v[44:45], v[24:25]
	v_pk_mul_f32 v[26:27], v[38:39], v[26:27]
	v_pk_mul_f32 v[24:25], v[36:37], v[24:25]
	ds_read_b128 v[36:39], v94 offset:61056
	s_waitcnt lgkmcnt(0)
	v_pk_mul_f32 v[42:43], v[54:55], v[38:39]
	v_pk_mul_f32 v[40:41], v[52:53], v[36:37]
	v_pk_mul_f32 v[46:47], v[58:59], v[38:39]
	v_pk_mul_f32 v[44:45], v[56:57], v[36:37]
	v_pk_mul_f32 v[38:39], v[50:51], v[38:39]
	v_pk_mul_f32 v[36:37], v[48:49], v[36:37]
	ds_read_b128 v[48:51], v94 offset:61120
	s_waitcnt lgkmcnt(0)
	s_barrier
	v_pk_mul_f32 v[2:3], v[2:3], v[50:51]
	v_pk_mul_f32 v[0:1], v[0:1], v[48:49]
	v_pk_mul_f32 v[6:7], v[6:7], v[50:51]
	v_pk_mul_f32 v[4:5], v[4:5], v[48:49]
	v_pk_mul_f32 v[10:11], v[10:11], v[50:51]
	v_pk_mul_f32 v[8:9], v[8:9], v[48:49]
	ds_read_b64_tr_b16 v[48:49], v68 offset:25600
	ds_read_b64_tr_b16 v[50:51], v68 offset:27200
	ds_read_b64_tr_b16 v[52:53], v69 offset:25600
	ds_read_b64_tr_b16 v[54:55], v69 offset:27200
	ds_read_b64_tr_b16 v[56:57], v70 offset:25600
	ds_read_b64_tr_b16 v[58:59], v70 offset:27200
	ds_read_b128 v[60:63], v166 offset:51200
	s_waitcnt lgkmcnt(0)
	v_mfma_f32_16x16x32_bf16 v[16:19], v[60:63], v[48:51], v[16:19]
	v_mfma_f32_16x16x32_bf16 v[20:23], v[60:63], v[52:55], v[20:23]
	v_mfma_f32_16x16x32_bf16 v[12:15], v[60:63], v[56:59], v[12:15]
	ds_read_b128 v[60:63], v166 offset:53504
	s_waitcnt lgkmcnt(0)
	v_mfma_f32_16x16x32_bf16 v[64:67], v[60:63], v[52:55], v[32:35]
	s_nop 2
	ds_read_b128 v[32:35], v166 offset:55808
	s_waitcnt lgkmcnt(0)
	v_mfma_f32_16x16x32_bf16 v[40:43], v[32:35], v[48:51], v[40:43]
	v_mfma_f32_16x16x32_bf16 v[44:47], v[32:35], v[52:55], v[44:47]
	v_mfma_f32_16x16x32_bf16 v[36:39], v[32:35], v[56:59], v[36:39]
	ds_read_b128 v[32:35], v166 offset:58112
	v_mfma_f32_16x16x32_bf16 v[28:31], v[60:63], v[48:51], v[28:31]
	v_mfma_f32_16x16x32_bf16 v[24:27], v[60:63], v[56:59], v[24:27]
	s_waitcnt lgkmcnt(0)
	v_mfma_f32_16x16x32_bf16 v[0:3], v[32:35], v[48:51], v[0:3]
	v_mfma_f32_16x16x32_bf16 v[4:7], v[32:35], v[52:55], v[4:7]
	v_mfma_f32_16x16x32_bf16 v[48:51], v[32:35], v[56:59], v[8:11]
	s_nop 2
	ds_read_b64_tr_b16 v[8:9], v68 offset:38400
	ds_read_b64_tr_b16 v[10:11], v68 offset:40000
	ds_read_b64_tr_b16 v[52:53], v69 offset:38400
	ds_read_b64_tr_b16 v[54:55], v69 offset:40000
	ds_read_b64_tr_b16 v[56:57], v70 offset:38400
	ds_read_b64_tr_b16 v[58:59], v70 offset:40000
	ds_read_b128 v[32:35], v166 offset:51264
	s_waitcnt lgkmcnt(0)
	v_mfma_f32_16x16x32_bf16 v[72:75], v[32:35], v[56:59], v[12:15]
	s_nop 2
	ds_read_b128 v[12:15], v166 offset:53568
	v_mfma_f32_16x16x32_bf16 v[60:63], v[32:35], v[8:11], v[16:19]
	v_mfma_f32_16x16x32_bf16 v[68:71], v[32:35], v[52:55], v[20:23]
	s_waitcnt lgkmcnt(0)
	v_mfma_f32_16x16x32_bf16 v[32:35], v[12:15], v[8:11], v[28:31]
	v_mfma_f32_16x16x32_bf16 v[28:31], v[12:15], v[52:55], v[64:67]
	v_mfma_f32_16x16x32_bf16 v[24:27], v[12:15], v[56:59], v[24:27]
	ds_read_b128 v[12:15], v166 offset:55872
	s_waitcnt lgkmcnt(0)
	v_mfma_f32_16x16x32_bf16 v[20:23], v[12:15], v[8:11], v[40:43]
	v_mfma_f32_16x16x32_bf16 v[16:19], v[12:15], v[52:55], v[44:47]
	v_mfma_f32_16x16x32_bf16 v[12:15], v[12:15], v[56:59], v[36:39]
	s_nop 2
	ds_read_b128 v[36:39], v166 offset:58176
	s_waitcnt lgkmcnt(0)
	v_mfma_f32_16x16x32_bf16 v[8:11], v[36:39], v[8:11], v[0:3]
	s_barrier
	v_mfma_f32_16x16x32_bf16 v[4:7], v[36:39], v[52:55], v[4:7]
	v_mfma_f32_16x16x32_bf16 v[0:3], v[36:39], v[56:59], v[48:51]
	ds_read_b32 v36, v94 offset:61440
	v_add_u32_e32 v38, s63, v142
	s_waitcnt lgkmcnt(0)
	v_mul_f32_e32 v37, v60, v36
	ds_write_b32 v38, v37
	v_mul_f32_e32 v37, v68, v36
	v_add_u32_e32 v38, s36, v142
	ds_write_b32 v38, v37
	v_mul_f32_e32 v36, v72, v36
	v_add_u32_e32 v37, s37, v142
	ds_write_b32 v37, v36
	ds_read_b32 v36, v94 offset:61444
	v_add_u32_e32 v38, s63, v143
	s_waitcnt lgkmcnt(0)
	v_mul_f32_e32 v37, v61, v36
	ds_write_b32 v38, v37
	v_mul_f32_e32 v37, v69, v36
	v_add_u32_e32 v38, s36, v143
	ds_write_b32 v38, v37
	v_mul_f32_e32 v36, v73, v36
	v_add_u32_e32 v37, s37, v143
	ds_write_b32 v37, v36
	ds_read_b32 v36, v94 offset:61448
	v_add_u32_e32 v38, s63, v144
	s_waitcnt lgkmcnt(0)
	v_mul_f32_e32 v37, v62, v36
	ds_write_b32 v38, v37
	v_mul_f32_e32 v37, v70, v36
	v_add_u32_e32 v38, s36, v144
	ds_write_b32 v38, v37
	v_mul_f32_e32 v36, v74, v36
	v_add_u32_e32 v37, s37, v144
	ds_write_b32 v37, v36
	ds_read_b32 v36, v94 offset:61452
	v_add_u32_e32 v38, s63, v145
	s_waitcnt lgkmcnt(0)
	v_mul_f32_e32 v37, v63, v36
	ds_write_b32 v38, v37
	v_mul_f32_e32 v37, v71, v36
	v_add_u32_e32 v38, s36, v145
	ds_write_b32 v38, v37
	v_mul_f32_e32 v36, v75, v36
	v_add_u32_e32 v37, s37, v145
	ds_write_b32 v37, v36
	ds_read_b32 v36, v94 offset:61504
	v_add_u32_e32 v37, s63, v146
	s_waitcnt lgkmcnt(0)
	v_mul_f32_e32 v32, v32, v36
	ds_write_b32 v37, v32
	v_mul_f32_e32 v28, v28, v36
	v_add_u32_e32 v32, s36, v146
	ds_write_b32 v32, v28
	v_mul_f32_e32 v24, v24, v36
	v_add_u32_e32 v28, s37, v146
	ds_write_b32 v28, v24
	ds_read_b32 v24, v94 offset:61508
	v_add_u32_e32 v32, s63, v147
	s_waitcnt lgkmcnt(0)
	v_mul_f32_e32 v28, v33, v24
	ds_write_b32 v32, v28
	v_mul_f32_e32 v28, v29, v24
	v_add_u32_e32 v29, s36, v147
	v_mul_f32_e32 v24, v25, v24
	v_add_u32_e32 v25, s37, v147
	ds_write_b32 v29, v28
	ds_write_b32 v25, v24
	ds_read_b32 v24, v94 offset:61512
	v_add_u32_e32 v28, s63, v148
	s_waitcnt lgkmcnt(0)
	v_mul_f32_e32 v25, v34, v24
	ds_write_b32 v28, v25
	v_mul_f32_e32 v25, v30, v24
	v_add_u32_e32 v28, s36, v148
	ds_write_b32 v28, v25
	v_mul_f32_e32 v24, v26, v24
	v_add_u32_e32 v25, s37, v148
	ds_write_b32 v25, v24
	ds_read_b32 v24, v94 offset:61516
	v_add_u32_e32 v26, s63, v149
	s_waitcnt lgkmcnt(0)
	v_mul_f32_e32 v25, v35, v24
	ds_write_b32 v26, v25
	v_mul_f32_e32 v25, v31, v24
	v_add_u32_e32 v26, s36, v149
	ds_write_b32 v26, v25
	v_mul_f32_e32 v24, v27, v24
	v_add_u32_e32 v25, s37, v149
	ds_write_b32 v25, v24
	ds_read_b32 v24, v94 offset:61568
	v_add_u32_e32 v25, s63, v150
	s_waitcnt lgkmcnt(0)
	v_mul_f32_e32 v20, v20, v24
	ds_write_b32 v25, v20
	v_mul_f32_e32 v16, v16, v24
	v_add_u32_e32 v20, s36, v150
	ds_write_b32 v20, v16
	v_mul_f32_e32 v12, v12, v24
	v_add_u32_e32 v16, s37, v150
	ds_write_b32 v16, v12
	ds_read_b32 v12, v94 offset:61572
	v_add_u32_e32 v20, s63, v151
	s_waitcnt lgkmcnt(0)
	v_mul_f32_e32 v16, v21, v12
	ds_write_b32 v20, v16
	v_mul_f32_e32 v16, v17, v12
	v_add_u32_e32 v17, s36, v151
	v_mul_f32_e32 v12, v13, v12
	v_add_u32_e32 v13, s37, v151
	ds_write_b32 v17, v16
	ds_write_b32 v13, v12
	ds_read_b32 v12, v94 offset:61576
	v_add_u32_e32 v16, s63, v152
	s_waitcnt lgkmcnt(0)
	v_mul_f32_e32 v13, v22, v12
	ds_write_b32 v16, v13
	v_mul_f32_e32 v13, v18, v12
	v_add_u32_e32 v16, s36, v152
	ds_write_b32 v16, v13
	v_mul_f32_e32 v12, v14, v12
	v_add_u32_e32 v13, s37, v152
	ds_write_b32 v13, v12
	ds_read_b32 v12, v94 offset:61580
	v_add_u32_e32 v14, s63, v153
	s_waitcnt lgkmcnt(0)
	v_mul_f32_e32 v13, v23, v12
	ds_write_b32 v14, v13
	v_mul_f32_e32 v13, v19, v12
	v_add_u32_e32 v14, s36, v153
	ds_write_b32 v14, v13
	v_mul_f32_e32 v12, v15, v12
	v_add_u32_e32 v13, s37, v153
	ds_write_b32 v13, v12
	ds_read_b32 v12, v94 offset:61632
	v_add_u32_e32 v13, s63, v154
	s_waitcnt lgkmcnt(0)
	v_mul_f32_e32 v8, v8, v12
	ds_write_b32 v13, v8
	v_mul_f32_e32 v4, v4, v12
	v_add_u32_e32 v8, s36, v154
	ds_write_b32 v8, v4
	v_mul_f32_e32 v0, v0, v12
	v_add_u32_e32 v4, s37, v154
	ds_write_b32 v4, v0
	ds_read_b32 v0, v94 offset:61636
	v_add_u32_e32 v8, s63, v155
	s_waitcnt lgkmcnt(0)
	v_mul_f32_e32 v4, v9, v0
	ds_write_b32 v8, v4
	v_mul_f32_e32 v4, v5, v0
	v_add_u32_e32 v5, s36, v155
	v_mul_f32_e32 v0, v1, v0
	v_add_u32_e32 v1, s37, v155
	ds_write_b32 v5, v4
	ds_write_b32 v1, v0
	ds_read_b32 v0, v94 offset:61640
	v_add_u32_e32 v4, s63, v156
	s_waitcnt lgkmcnt(0)
	v_mul_f32_e32 v1, v10, v0
	ds_write_b32 v4, v1
	v_mul_f32_e32 v1, v6, v0
	v_add_u32_e32 v4, s36, v156
	ds_write_b32 v4, v1
	v_mul_f32_e32 v0, v2, v0
	v_add_u32_e32 v1, s37, v156
	ds_write_b32 v1, v0
	ds_read_b32 v0, v94 offset:61644
	v_add_u32_e32 v2, s63, v157
	s_waitcnt lgkmcnt(0)
	v_mul_f32_e32 v1, v11, v0
	ds_write_b32 v2, v1
	v_mul_f32_e32 v1, v7, v0
	v_add_u32_e32 v2, s36, v157
	ds_write_b32 v2, v1
	v_mul_f32_e32 v0, v3, v0
	v_add_u32_e32 v1, s37, v157
	ds_write_b32 v1, v0
	ds_write_b32 v101, v246 offset:62464
	v_or_b32_e32 v202, v125, v108
	v_mov_b64_e32 v[200:201], s[60:61]
	v_mad_u64_u32 v[200:201], vcc, v202, s50, v[200:201]
	v_mov_b32_e32 v202, v201
	v_mad_u64_u32 v[202:203], vcc, v127, s50, v[202:203]
	v_mov_b32_e32 v201, v202
	v_lshl_add_u64 v[200:201], v[200:201], 0, v[90:91]
	v_mov_b32_e32 v202, v124
	v_mov_b32_e32 v203, v91
	v_lshl_add_u64 v[200:201], v[200:201], 0, v[202:203]
	v_lshl_add_u64 v[200:201], v[200:201], 0, s[34:35]
	global_load_dwordx4 v[206:209], v[200:201], off
	global_load_dwordx4 v[210:213], v[200:201], off offset:16
	global_load_dwordx4 v[214:217], v[200:201], off offset:32
	global_load_dwordx4 v[218:221], v[200:201], off offset:48
	global_load_dwordx4 v[222:225], v[200:201], off offset:64
	global_load_dwordx4 v[226:229], v[200:201], off offset:80
	s_waitcnt lgkmcnt(0)
	s_barrier
	ds_read_b128 v[8:11], v167
	ds_read_b128 v[18:21], v167 offset:16
	ds_read_b128 v[22:25], v167 offset:32
	ds_read_b128 v[4:7], v167 offset:48
	s_waitcnt lgkmcnt(3)
	v_mul_f32_e32 v0, v9, v9
	v_pk_fma_f32 v[0:1], v[8:9], v[8:9], v[0:1] op_sel_hi:[1,1,0]
	s_waitcnt lgkmcnt(1)
	v_mul_f32_e32 v2, v22, v22
	v_mov_b32_e32 v1, v2
	v_mul_f32_e32 v2, v11, v11
	v_mul_f32_e32 v12, v23, v23
	v_pk_fma_f32 v[2:3], v[10:11], v[10:11], v[2:3] op_sel_hi:[1,1,0]
	v_mul_f32_e32 v13, v24, v24
	v_mov_b32_e32 v3, v12
	v_pk_add_f32 v[0:1], v[0:1], v[2:3]
	v_mul_f32_e32 v2, v19, v19
	v_pk_fma_f32 v[2:3], v[18:19], v[18:19], v[2:3] op_sel_hi:[1,1,0]
	v_mul_f32_e32 v12, v21, v21
	v_mul_f32_e32 v14, v25, v25
	v_mov_b32_e32 v3, v13
	v_pk_fma_f32 v[12:13], v[20:21], v[20:21], v[12:13] op_sel_hi:[1,1,0]
	s_nop 0
	v_mov_b32_e32 v13, v14
	v_pk_add_f32 v[2:3], v[2:3], v[12:13]
	s_nop 0
	v_pk_add_f32 v[16:17], v[0:1], v[2:3]
	s_waitcnt lgkmcnt(0)
	v_pk_mul_f32 v[0:1], v[6:7], v[6:7]
	v_pk_mul_f32 v[2:3], v[4:5], v[4:5]
	s_nop 0
	v_pk_mov_b32 v[12:13], v[2:3], v[0:1] op_sel:[1,0]
	v_mov_b32_e32 v3, v1
	v_pk_add_f32 v[26:27], v[12:13], v[2:3]
	ds_read_b128 v[0:3], v167 offset:64
	ds_read_b128 v[12:15], v167 offset:80
	s_waitcnt lgkmcnt(0)
	v_mul_f32_e32 v28, v12, v12
	v_mul_f32_e32 v29, v13, v13
	v_mul_f32_e32 v30, v14, v14
	v_mul_f32_e32 v31, v15, v15
	v_pk_add_f32 v[12:13], v[16:17], v[16:17] op_sel:[0,1] op_sel_hi:[1,0]
	v_pk_add_f32 v[14:15], v[26:27], v[26:27] op_sel:[0,1] op_sel_hi:[1,0]
	v_mov_b32_e32 v13, v28
	v_mov_b32_e32 v15, v29
	v_pk_add_f32 v[12:13], v[12:13], v[14:15]
	v_mul_f32_e32 v14, v1, v1
	v_pk_fma_f32 v[0:1], v[0:1], v[0:1], v[14:15] op_sel_hi:[1,1,0]
	v_mul_f32_e32 v14, v3, v3
	v_pk_fma_f32 v[2:3], v[2:3], v[2:3], v[14:15] op_sel_hi:[1,1,0]
	v_mov_b32_e32 v1, v30
	v_mov_b32_e32 v3, v31
	v_pk_add_f32 v[0:1], v[0:1], v[2:3]
	s_nop 0
	v_pk_add_f32 v[16:17], v[12:13], v[0:1]
	ds_read_b128 v[0:3], v167 offset:96
	s_waitcnt lgkmcnt(0)
	v_pk_mul_f32 v[2:3], v[2:3], v[2:3]
	v_pk_mul_f32 v[0:1], v[0:1], v[0:1]
	s_nop 0
	v_pk_mov_b32 v[12:13], v[0:1], v[2:3] op_sel:[1,0]
	v_mov_b32_e32 v1, v3
	v_pk_add_f32 v[26:27], v[12:13], v[0:1]
	ds_read_b128 v[0:3], v167 offset:112
	ds_read_b128 v[12:15], v167 offset:128
	s_waitcnt lgkmcnt(0)
	v_mul_f32_e32 v28, v12, v12
	v_mul_f32_e32 v29, v13, v13
	v_mul_f32_e32 v30, v14, v14
	v_mul_f32_e32 v31, v15, v15
	v_pk_add_f32 v[12:13], v[16:17], v[16:17] op_sel:[0,1] op_sel_hi:[1,0]
	v_pk_add_f32 v[14:15], v[26:27], v[26:27] op_sel:[0,1] op_sel_hi:[1,0]
	v_mov_b32_e32 v13, v28
	v_mov_b32_e32 v15, v29
	v_pk_add_f32 v[12:13], v[12:13], v[14:15]
	v_mul_f32_e32 v14, v1, v1
	v_pk_fma_f32 v[0:1], v[0:1], v[0:1], v[14:15] op_sel_hi:[1,1,0]
	v_mul_f32_e32 v14, v3, v3
	v_pk_fma_f32 v[2:3], v[2:3], v[2:3], v[14:15] op_sel_hi:[1,1,0]
	v_mov_b32_e32 v1, v30
	v_mov_b32_e32 v3, v31
	v_pk_add_f32 v[0:1], v[0:1], v[2:3]
	s_nop 0
	v_pk_add_f32 v[16:17], v[12:13], v[0:1]
	ds_read_b128 v[0:3], v167 offset:144
	s_waitcnt lgkmcnt(0)
	v_pk_mul_f32 v[2:3], v[2:3], v[2:3]
	v_pk_mul_f32 v[0:1], v[0:1], v[0:1]
	s_nop 0
	v_pk_mov_b32 v[12:13], v[0:1], v[2:3] op_sel:[1,0]
	v_mov_b32_e32 v1, v3
	v_pk_add_f32 v[26:27], v[12:13], v[0:1]
	ds_read_b128 v[0:3], v167 offset:160
	ds_read_b128 v[12:15], v167 offset:176
	s_waitcnt lgkmcnt(0)
	v_mul_f32_e32 v28, v12, v12
	v_mul_f32_e32 v29, v13, v13
	v_mul_f32_e32 v30, v14, v14
	v_mul_f32_e32 v31, v15, v15
	v_pk_add_f32 v[12:13], v[16:17], v[16:17] op_sel:[0,1] op_sel_hi:[1,0]
	v_pk_add_f32 v[14:15], v[26:27], v[26:27] op_sel:[0,1] op_sel_hi:[1,0]
	v_mov_b32_e32 v13, v28
	v_mov_b32_e32 v15, v29
	v_pk_add_f32 v[12:13], v[12:13], v[14:15]
	v_mul_f32_e32 v14, v1, v1
	v_pk_fma_f32 v[0:1], v[0:1], v[0:1], v[14:15] op_sel_hi:[1,1,0]
	v_mul_f32_e32 v14, v3, v3
	v_pk_fma_f32 v[2:3], v[2:3], v[2:3], v[14:15] op_sel_hi:[1,1,0]
	v_mov_b32_e32 v1, v30
	v_mov_b32_e32 v3, v31
	v_pk_add_f32 v[0:1], v[0:1], v[2:3]
	v_pk_add_f32 v[0:1], v[12:13], v[0:1]
	v_add_f32_e32 v0, v0, v1
	ds_bpermute_b32 v1, v139, v0
	s_waitcnt lgkmcnt(0)
	v_add_f32_e32 v0, v0, v1
	ds_bpermute_b32 v1, v140, v0
	s_waitcnt lgkmcnt(0)
	v_add_f32_e32 v0, v0, v1
	v_fmamk_f32 v0, v0, 0x3baaaaab, v168
	v_cmp_gt_f32_e32 vcc, s55, v0
	v_mul_f32_e32 v1, 0x4b800000, v0
	s_nop 0
	v_cndmask_b32_e32 v0, v0, v1, vcc
	v_rsq_f32_e32 v0, v0
	s_nop 0
	v_mul_f32_e32 v1, 0x45800000, v0
	v_cndmask_b32_e32 v14, v0, v1, vcc
	s_waitcnt vmcnt(0)
	ds_read_b128 v[0:3], v167 offset:0
	ds_read_b128 v[4:7], v167 offset:16
	ds_read_b128 v[16:19], v138 offset:62464
	ds_read_b128 v[20:23], v138 offset:62480
	ds_read_b128 v[32:35], v167 offset:32
	ds_read_b128 v[36:39], v167 offset:48
	ds_read_b128 v[40:43], v138 offset:62496
	ds_read_b128 v[44:47], v138 offset:62512
	v_lshlrev_b32_e32 v24, 16, v206
	v_and_b32_e32 v25, 0xffff0000, v206
	v_lshlrev_b32_e32 v26, 16, v207
	v_and_b32_e32 v27, 0xffff0000, v207
	v_lshlrev_b32_e32 v28, 16, v208
	v_and_b32_e32 v29, 0xffff0000, v208
	v_lshlrev_b32_e32 v30, 16, v209
	v_and_b32_e32 v31, 0xffff0000, v209
	v_mul_f32_e32 v24, 0xbfb8aa3b, v24
	v_mul_f32_e32 v25, 0xbfb8aa3b, v25
	v_mul_f32_e32 v26, 0xbfb8aa3b, v26
	v_mul_f32_e32 v27, 0xbfb8aa3b, v27
	v_mul_f32_e32 v28, 0xbfb8aa3b, v28
	v_mul_f32_e32 v29, 0xbfb8aa3b, v29
	v_mul_f32_e32 v30, 0xbfb8aa3b, v30
	v_mul_f32_e32 v31, 0xbfb8aa3b, v31
	v_exp_f32_e32 v24, v24
	v_exp_f32_e32 v25, v25
	v_exp_f32_e32 v26, v26
	v_exp_f32_e32 v27, v27
	v_exp_f32_e32 v28, v28
	v_exp_f32_e32 v29, v29
	v_exp_f32_e32 v30, v30
	v_exp_f32_e32 v31, v31
	v_add_f32_e32 v24, 1.0, v24
	v_add_f32_e32 v25, 1.0, v25
	v_add_f32_e32 v26, 1.0, v26
	v_add_f32_e32 v27, 1.0, v27
	v_add_f32_e32 v28, 1.0, v28
	v_add_f32_e32 v29, 1.0, v29
	v_add_f32_e32 v30, 1.0, v30
	v_add_f32_e32 v31, 1.0, v31
	v_rcp_f32_e32 v24, v24
	v_rcp_f32_e32 v25, v25
	v_rcp_f32_e32 v26, v26
	v_rcp_f32_e32 v27, v27
	v_rcp_f32_e32 v28, v28
	v_rcp_f32_e32 v29, v29
	v_rcp_f32_e32 v30, v30
	v_rcp_f32_e32 v31, v31
	s_waitcnt lgkmcnt(4)
	v_pk_mul_f32 v[0:1], v[0:1], v[14:15] op_sel_hi:[1,0]
	v_pk_mul_f32 v[2:3], v[2:3], v[14:15] op_sel_hi:[1,0]
	v_pk_mul_f32 v[4:5], v[4:5], v[14:15] op_sel_hi:[1,0]
	v_pk_mul_f32 v[6:7], v[6:7], v[14:15] op_sel_hi:[1,0]
	v_pk_mul_f32 v[0:1], v[16:17], v[0:1]
	v_pk_mul_f32 v[2:3], v[18:19], v[2:3]
	v_pk_mul_f32 v[4:5], v[20:21], v[4:5]
	v_pk_mul_f32 v[6:7], v[22:23], v[6:7]
	v_pk_mul_f32 v[0:1], v[24:25], v[0:1]
	v_pk_mul_f32 v[2:3], v[26:27], v[2:3]
	v_pk_mul_f32 v[4:5], v[28:29], v[4:5]
	v_pk_mul_f32 v[6:7], v[30:31], v[6:7]
	v_cvt_pk_bf16_f32 v8, v0, v1
	v_cvt_pk_bf16_f32 v9, v2, v3
	v_cvt_pk_bf16_f32 v10, v4, v5
	v_cvt_pk_bf16_f32 v11, v6, v7
	global_store_dwordx4 v[200:201], v[8:11], off
	ds_read_b128 v[0:3], v167 offset:64
	ds_read_b128 v[4:7], v167 offset:80
	ds_read_b128 v[16:19], v138 offset:62528
	ds_read_b128 v[20:23], v138 offset:62544
	v_lshlrev_b32_e32 v24, 16, v210
	v_and_b32_e32 v25, 0xffff0000, v210
	v_lshlrev_b32_e32 v26, 16, v211
	v_and_b32_e32 v27, 0xffff0000, v211
	v_lshlrev_b32_e32 v28, 16, v212
	v_and_b32_e32 v29, 0xffff0000, v212
	v_lshlrev_b32_e32 v30, 16, v213
	v_and_b32_e32 v31, 0xffff0000, v213
	v_mul_f32_e32 v24, 0xbfb8aa3b, v24
	v_mul_f32_e32 v25, 0xbfb8aa3b, v25
	v_mul_f32_e32 v26, 0xbfb8aa3b, v26
	v_mul_f32_e32 v27, 0xbfb8aa3b, v27
	v_mul_f32_e32 v28, 0xbfb8aa3b, v28
	v_mul_f32_e32 v29, 0xbfb8aa3b, v29
	v_mul_f32_e32 v30, 0xbfb8aa3b, v30
	v_mul_f32_e32 v31, 0xbfb8aa3b, v31
	v_exp_f32_e32 v24, v24
	v_exp_f32_e32 v25, v25
	v_exp_f32_e32 v26, v26
	v_exp_f32_e32 v27, v27
	v_exp_f32_e32 v28, v28
	v_exp_f32_e32 v29, v29
	v_exp_f32_e32 v30, v30
	v_exp_f32_e32 v31, v31
	v_add_f32_e32 v24, 1.0, v24
	v_add_f32_e32 v25, 1.0, v25
	v_add_f32_e32 v26, 1.0, v26
	v_add_f32_e32 v27, 1.0, v27
	v_add_f32_e32 v28, 1.0, v28
	v_add_f32_e32 v29, 1.0, v29
	v_add_f32_e32 v30, 1.0, v30
	v_add_f32_e32 v31, 1.0, v31
	v_rcp_f32_e32 v24, v24
	v_rcp_f32_e32 v25, v25
	v_rcp_f32_e32 v26, v26
	v_rcp_f32_e32 v27, v27
	v_rcp_f32_e32 v28, v28
	v_rcp_f32_e32 v29, v29
	v_rcp_f32_e32 v30, v30
	v_rcp_f32_e32 v31, v31
	s_waitcnt lgkmcnt(4)
	v_pk_mul_f32 v[32:33], v[32:33], v[14:15] op_sel_hi:[1,0]
	v_pk_mul_f32 v[34:35], v[34:35], v[14:15] op_sel_hi:[1,0]
	v_pk_mul_f32 v[36:37], v[36:37], v[14:15] op_sel_hi:[1,0]
	v_pk_mul_f32 v[38:39], v[38:39], v[14:15] op_sel_hi:[1,0]
	v_pk_mul_f32 v[32:33], v[40:41], v[32:33]
	v_pk_mul_f32 v[34:35], v[42:43], v[34:35]
	v_pk_mul_f32 v[36:37], v[44:45], v[36:37]
	v_pk_mul_f32 v[38:39], v[46:47], v[38:39]
	v_pk_mul_f32 v[32:33], v[24:25], v[32:33]
	v_pk_mul_f32 v[34:35], v[26:27], v[34:35]
	v_pk_mul_f32 v[36:37], v[28:29], v[36:37]
	v_pk_mul_f32 v[38:39], v[30:31], v[38:39]
	v_cvt_pk_bf16_f32 v8, v32, v33
	v_cvt_pk_bf16_f32 v9, v34, v35
	v_cvt_pk_bf16_f32 v10, v36, v37
	v_cvt_pk_bf16_f32 v11, v38, v39
	global_store_dwordx4 v[200:201], v[8:11], off offset:16
	ds_read_b128 v[32:35], v167 offset:96
	ds_read_b128 v[36:39], v167 offset:112
	ds_read_b128 v[40:43], v138 offset:62560
	ds_read_b128 v[44:47], v138 offset:62576
	v_lshlrev_b32_e32 v24, 16, v214
	v_and_b32_e32 v25, 0xffff0000, v214
	v_lshlrev_b32_e32 v26, 16, v215
	v_and_b32_e32 v27, 0xffff0000, v215
	v_lshlrev_b32_e32 v28, 16, v216
	v_and_b32_e32 v29, 0xffff0000, v216
	v_lshlrev_b32_e32 v30, 16, v217
	v_and_b32_e32 v31, 0xffff0000, v217
	v_mul_f32_e32 v24, 0xbfb8aa3b, v24
	v_mul_f32_e32 v25, 0xbfb8aa3b, v25
	v_mul_f32_e32 v26, 0xbfb8aa3b, v26
	v_mul_f32_e32 v27, 0xbfb8aa3b, v27
	v_mul_f32_e32 v28, 0xbfb8aa3b, v28
	v_mul_f32_e32 v29, 0xbfb8aa3b, v29
	v_mul_f32_e32 v30, 0xbfb8aa3b, v30
	v_mul_f32_e32 v31, 0xbfb8aa3b, v31
	v_exp_f32_e32 v24, v24
	v_exp_f32_e32 v25, v25
	v_exp_f32_e32 v26, v26
	v_exp_f32_e32 v27, v27
	v_exp_f32_e32 v28, v28
	v_exp_f32_e32 v29, v29
	v_exp_f32_e32 v30, v30
	v_exp_f32_e32 v31, v31
	v_add_f32_e32 v24, 1.0, v24
	v_add_f32_e32 v25, 1.0, v25
	v_add_f32_e32 v26, 1.0, v26
	v_add_f32_e32 v27, 1.0, v27
	v_add_f32_e32 v28, 1.0, v28
	v_add_f32_e32 v29, 1.0, v29
	v_add_f32_e32 v30, 1.0, v30
	v_add_f32_e32 v31, 1.0, v31
	v_rcp_f32_e32 v24, v24
	v_rcp_f32_e32 v25, v25
	v_rcp_f32_e32 v26, v26
	v_rcp_f32_e32 v27, v27
	v_rcp_f32_e32 v28, v28
	v_rcp_f32_e32 v29, v29
	v_rcp_f32_e32 v30, v30
	v_rcp_f32_e32 v31, v31
	s_waitcnt lgkmcnt(4)
	v_pk_mul_f32 v[0:1], v[0:1], v[14:15] op_sel_hi:[1,0]
	v_pk_mul_f32 v[2:3], v[2:3], v[14:15] op_sel_hi:[1,0]
	v_pk_mul_f32 v[4:5], v[4:5], v[14:15] op_sel_hi:[1,0]
	v_pk_mul_f32 v[6:7], v[6:7], v[14:15] op_sel_hi:[1,0]
	v_pk_mul_f32 v[0:1], v[16:17], v[0:1]
	v_pk_mul_f32 v[2:3], v[18:19], v[2:3]
	v_pk_mul_f32 v[4:5], v[20:21], v[4:5]
	v_pk_mul_f32 v[6:7], v[22:23], v[6:7]
	v_pk_mul_f32 v[0:1], v[24:25], v[0:1]
	v_pk_mul_f32 v[2:3], v[26:27], v[2:3]
	v_pk_mul_f32 v[4:5], v[28:29], v[4:5]
	v_pk_mul_f32 v[6:7], v[30:31], v[6:7]
	v_cvt_pk_bf16_f32 v8, v0, v1
	v_cvt_pk_bf16_f32 v9, v2, v3
	v_cvt_pk_bf16_f32 v10, v4, v5
	v_cvt_pk_bf16_f32 v11, v6, v7
	global_store_dwordx4 v[200:201], v[8:11], off offset:32
	ds_read_b128 v[0:3], v167 offset:128
	ds_read_b128 v[4:7], v167 offset:144
	ds_read_b128 v[16:19], v138 offset:62592
	ds_read_b128 v[20:23], v138 offset:62608
	v_lshlrev_b32_e32 v24, 16, v218
	v_and_b32_e32 v25, 0xffff0000, v218
	v_lshlrev_b32_e32 v26, 16, v219
	v_and_b32_e32 v27, 0xffff0000, v219
	v_lshlrev_b32_e32 v28, 16, v220
	v_and_b32_e32 v29, 0xffff0000, v220
	v_lshlrev_b32_e32 v30, 16, v221
	v_and_b32_e32 v31, 0xffff0000, v221
	v_mul_f32_e32 v24, 0xbfb8aa3b, v24
	v_mul_f32_e32 v25, 0xbfb8aa3b, v25
	v_mul_f32_e32 v26, 0xbfb8aa3b, v26
	v_mul_f32_e32 v27, 0xbfb8aa3b, v27
	v_mul_f32_e32 v28, 0xbfb8aa3b, v28
	v_mul_f32_e32 v29, 0xbfb8aa3b, v29
	v_mul_f32_e32 v30, 0xbfb8aa3b, v30
	v_mul_f32_e32 v31, 0xbfb8aa3b, v31
	v_exp_f32_e32 v24, v24
	v_exp_f32_e32 v25, v25
	v_exp_f32_e32 v26, v26
	v_exp_f32_e32 v27, v27
	v_exp_f32_e32 v28, v28
	v_exp_f32_e32 v29, v29
	v_exp_f32_e32 v30, v30
	v_exp_f32_e32 v31, v31
	v_add_f32_e32 v24, 1.0, v24
	v_add_f32_e32 v25, 1.0, v25
	v_add_f32_e32 v26, 1.0, v26
	v_add_f32_e32 v27, 1.0, v27
	v_add_f32_e32 v28, 1.0, v28
	v_add_f32_e32 v29, 1.0, v29
	v_add_f32_e32 v30, 1.0, v30
	v_add_f32_e32 v31, 1.0, v31
	v_rcp_f32_e32 v24, v24
	v_rcp_f32_e32 v25, v25
	v_rcp_f32_e32 v26, v26
	v_rcp_f32_e32 v27, v27
	v_rcp_f32_e32 v28, v28
	v_rcp_f32_e32 v29, v29
	v_rcp_f32_e32 v30, v30
	v_rcp_f32_e32 v31, v31
	s_waitcnt lgkmcnt(4)
	v_pk_mul_f32 v[32:33], v[32:33], v[14:15] op_sel_hi:[1,0]
	v_pk_mul_f32 v[34:35], v[34:35], v[14:15] op_sel_hi:[1,0]
	v_pk_mul_f32 v[36:37], v[36:37], v[14:15] op_sel_hi:[1,0]
	v_pk_mul_f32 v[38:39], v[38:39], v[14:15] op_sel_hi:[1,0]
	v_pk_mul_f32 v[32:33], v[40:41], v[32:33]
	v_pk_mul_f32 v[34:35], v[42:43], v[34:35]
	v_pk_mul_f32 v[36:37], v[44:45], v[36:37]
	v_pk_mul_f32 v[38:39], v[46:47], v[38:39]
	v_pk_mul_f32 v[32:33], v[24:25], v[32:33]
	v_pk_mul_f32 v[34:35], v[26:27], v[34:35]
	v_pk_mul_f32 v[36:37], v[28:29], v[36:37]
	v_pk_mul_f32 v[38:39], v[30:31], v[38:39]
	v_cvt_pk_bf16_f32 v8, v32, v33
	v_cvt_pk_bf16_f32 v9, v34, v35
	v_cvt_pk_bf16_f32 v10, v36, v37
	v_cvt_pk_bf16_f32 v11, v38, v39
	global_store_dwordx4 v[200:201], v[8:11], off offset:48
	ds_read_b128 v[32:35], v167 offset:160
	ds_read_b128 v[36:39], v167 offset:176
	ds_read_b128 v[40:43], v138 offset:62624
	ds_read_b128 v[44:47], v138 offset:62640
	v_lshlrev_b32_e32 v24, 16, v222
	v_and_b32_e32 v25, 0xffff0000, v222
	v_lshlrev_b32_e32 v26, 16, v223
	v_and_b32_e32 v27, 0xffff0000, v223
	v_lshlrev_b32_e32 v28, 16, v224
	v_and_b32_e32 v29, 0xffff0000, v224
	v_lshlrev_b32_e32 v30, 16, v225
	v_and_b32_e32 v31, 0xffff0000, v225
	v_mul_f32_e32 v24, 0xbfb8aa3b, v24
	v_mul_f32_e32 v25, 0xbfb8aa3b, v25
	v_mul_f32_e32 v26, 0xbfb8aa3b, v26
	v_mul_f32_e32 v27, 0xbfb8aa3b, v27
	v_mul_f32_e32 v28, 0xbfb8aa3b, v28
	v_mul_f32_e32 v29, 0xbfb8aa3b, v29
	v_mul_f32_e32 v30, 0xbfb8aa3b, v30
	v_mul_f32_e32 v31, 0xbfb8aa3b, v31
	v_exp_f32_e32 v24, v24
	v_exp_f32_e32 v25, v25
	v_exp_f32_e32 v26, v26
	v_exp_f32_e32 v27, v27
	v_exp_f32_e32 v28, v28
	v_exp_f32_e32 v29, v29
	v_exp_f32_e32 v30, v30
	v_exp_f32_e32 v31, v31
	v_add_f32_e32 v24, 1.0, v24
	v_add_f32_e32 v25, 1.0, v25
	v_add_f32_e32 v26, 1.0, v26
	v_add_f32_e32 v27, 1.0, v27
	v_add_f32_e32 v28, 1.0, v28
	v_add_f32_e32 v29, 1.0, v29
	v_add_f32_e32 v30, 1.0, v30
	v_add_f32_e32 v31, 1.0, v31
	v_rcp_f32_e32 v24, v24
	v_rcp_f32_e32 v25, v25
	v_rcp_f32_e32 v26, v26
	v_rcp_f32_e32 v27, v27
	v_rcp_f32_e32 v28, v28
	v_rcp_f32_e32 v29, v29
	v_rcp_f32_e32 v30, v30
	v_rcp_f32_e32 v31, v31
	s_waitcnt lgkmcnt(4)
	v_pk_mul_f32 v[0:1], v[0:1], v[14:15] op_sel_hi:[1,0]
	v_pk_mul_f32 v[2:3], v[2:3], v[14:15] op_sel_hi:[1,0]
	v_pk_mul_f32 v[4:5], v[4:5], v[14:15] op_sel_hi:[1,0]
	v_pk_mul_f32 v[6:7], v[6:7], v[14:15] op_sel_hi:[1,0]
	v_pk_mul_f32 v[0:1], v[16:17], v[0:1]
	v_pk_mul_f32 v[2:3], v[18:19], v[2:3]
	v_pk_mul_f32 v[4:5], v[20:21], v[4:5]
	v_pk_mul_f32 v[6:7], v[22:23], v[6:7]
	v_pk_mul_f32 v[0:1], v[24:25], v[0:1]
	v_pk_mul_f32 v[2:3], v[26:27], v[2:3]
	v_pk_mul_f32 v[4:5], v[28:29], v[4:5]
	v_pk_mul_f32 v[6:7], v[30:31], v[6:7]
	v_cvt_pk_bf16_f32 v8, v0, v1
	v_cvt_pk_bf16_f32 v9, v2, v3
	v_cvt_pk_bf16_f32 v10, v4, v5
	v_cvt_pk_bf16_f32 v11, v6, v7
	global_store_dwordx4 v[200:201], v[8:11], off offset:64
	v_lshlrev_b32_e32 v24, 16, v226
	v_and_b32_e32 v25, 0xffff0000, v226
	v_lshlrev_b32_e32 v26, 16, v227
	v_and_b32_e32 v27, 0xffff0000, v227
	v_lshlrev_b32_e32 v28, 16, v228
	v_and_b32_e32 v29, 0xffff0000, v228
	v_lshlrev_b32_e32 v30, 16, v229
	v_and_b32_e32 v31, 0xffff0000, v229
	v_mul_f32_e32 v24, 0xbfb8aa3b, v24
	v_mul_f32_e32 v25, 0xbfb8aa3b, v25
	v_mul_f32_e32 v26, 0xbfb8aa3b, v26
	v_mul_f32_e32 v27, 0xbfb8aa3b, v27
	v_mul_f32_e32 v28, 0xbfb8aa3b, v28
	v_mul_f32_e32 v29, 0xbfb8aa3b, v29
	v_mul_f32_e32 v30, 0xbfb8aa3b, v30
	v_mul_f32_e32 v31, 0xbfb8aa3b, v31
	v_exp_f32_e32 v24, v24
	v_exp_f32_e32 v25, v25
	v_exp_f32_e32 v26, v26
	v_exp_f32_e32 v27, v27
	v_exp_f32_e32 v28, v28
	v_exp_f32_e32 v29, v29
	v_exp_f32_e32 v30, v30
	v_exp_f32_e32 v31, v31
	v_add_f32_e32 v24, 1.0, v24
	v_add_f32_e32 v25, 1.0, v25
	v_add_f32_e32 v26, 1.0, v26
	v_add_f32_e32 v27, 1.0, v27
	v_add_f32_e32 v28, 1.0, v28
	v_add_f32_e32 v29, 1.0, v29
	v_add_f32_e32 v30, 1.0, v30
	v_add_f32_e32 v31, 1.0, v31
	v_rcp_f32_e32 v24, v24
	v_rcp_f32_e32 v25, v25
	v_rcp_f32_e32 v26, v26
	v_rcp_f32_e32 v27, v27
	v_rcp_f32_e32 v28, v28
	v_rcp_f32_e32 v29, v29
	v_rcp_f32_e32 v30, v30
	v_rcp_f32_e32 v31, v31
	s_waitcnt lgkmcnt(0)
	v_pk_mul_f32 v[32:33], v[32:33], v[14:15] op_sel_hi:[1,0]
	v_pk_mul_f32 v[34:35], v[34:35], v[14:15] op_sel_hi:[1,0]
	v_pk_mul_f32 v[36:37], v[36:37], v[14:15] op_sel_hi:[1,0]
	v_pk_mul_f32 v[38:39], v[38:39], v[14:15] op_sel_hi:[1,0]
	v_pk_mul_f32 v[32:33], v[40:41], v[32:33]
	v_pk_mul_f32 v[34:35], v[42:43], v[34:35]
	v_pk_mul_f32 v[36:37], v[44:45], v[36:37]
	v_pk_mul_f32 v[38:39], v[46:47], v[38:39]
	v_pk_mul_f32 v[32:33], v[24:25], v[32:33]
	v_pk_mul_f32 v[34:35], v[26:27], v[34:35]
	v_pk_mul_f32 v[36:37], v[28:29], v[36:37]
	v_pk_mul_f32 v[38:39], v[30:31], v[38:39]
	v_cvt_pk_bf16_f32 v8, v32, v33
	v_cvt_pk_bf16_f32 v9, v34, v35
	v_cvt_pk_bf16_f32 v10, v36, v37
	v_cvt_pk_bf16_f32 v11, v38, v39
	global_store_dwordx4 v[200:201], v[8:11], off offset:80
	s_cbranch_scc0 .LBB0_561
